# batch 16 serialized residual loads in fused LN epilogue (11 in flight, counted vmcnt)
# speedup vs baseline: 1.0041x; 1.0004x over previous
; #define LAS __attribute__((address_space(3)))
; __global__ void __launch_bounds__(NTHREADS, 2) mega_fwd(Args a) {
;     extern __shared__ __attribute__((aligned(16))) unsigned char lds_raw[];
;     LAS unsigned char* lds = (LAS unsigned char*)lds_raw;
;     const int G = gridDim.x, bid = blockIdx.x, ngw = G * NWAVES;
;     int cv = bid; bool grouped = false;
;     unsigned char* ws = a.ws;
;     bf16_t* XB = (bf16_t*)(ws + WS_XB); float* Y = (float*)(ws + WS_Y); bf16_t* BIG = (bf16_t*)(ws + WS_BIG);
;     bf16_t* DP = (bf16_t*)(ws + WS_DP); bf16_t* CAT = (bf16_t*)(ws + WS_CAT); bf16_t* VT = (bf16_t*)(ws + WS_VT);
;     float* X = a.out;
;     volatile LAS unsigned* misc = (volatile LAS unsigned*)(lds + MISC_OFF);
;     if (threadIdx.x < 16) misc[threadIdx.x] = 0u;
;     __syncthreads();
;     XcdBarrier xbar; xbar.bar = (unsigned*)(ws + WS_CTL); xbar.x = 0; xbar.st = misc;
;     if (a.ph_hi - a.ph_lo > 1) xbar = xcd_barrier_post((unsigned*)(ws + WS_CTL), misc);
_Z8mega_fwd4Args:
	s_mov_b32 s100, 0
	s_load_dwordx8 s[88:95], s[0:1], 0x60
	s_load_dwordx8 s[4:11], s[0:1], 0x40
	v_and_b32_e32 v188, 0x3ff, v0
	v_cmp_gt_u32_e32 vcc, 16, v188
	s_waitcnt lgkmcnt(0)
	v_writelane_b32 v253, s4, 0
	s_nop 1
	v_writelane_b32 v253, s5, 1
	v_writelane_b32 v253, s6, 2
	v_writelane_b32 v253, s7, 3
	v_writelane_b32 v253, s8, 4
	v_writelane_b32 v253, s9, 5
	v_writelane_b32 v253, s10, 6
	v_writelane_b32 v253, s11, 7
	s_load_dword s10, s[0:1], 0x80
	s_add_u32 s4, s0, 0x80
	s_addc_u32 s5, s1, 0
	v_writelane_b32 v253, s4, 8
	s_nop 1
	v_writelane_b32 v253, s5, 9
	s_and_saveexec_b64 s[12:13], vcc
	v_lshl_add_u32 v1, v188, 2, 0
	v_add_u32_e32 v1, 0x23fc0, v1
	v_mov_b32_e32 v2, 0
	ds_write_b32 v1, v2
	s_or_b64 exec, exec, s[12:13]
	s_add_u32 s18, s92, 0x23080000
	s_addc_u32 s19, s93, 0
	s_sub_i32 s3, s95, s94
	s_mov_b32 s4, 0
	s_cmp_gt_i32 s3, 1
	v_writelane_b32 v253, s4, 10
	s_cselect_b64 s[16:17], -1, 0
	s_cmp_lt_i32 s3, 2
	v_cmp_eq_u32_e32 vcc, 0, v188
	s_waitcnt lgkmcnt(0)
	s_barrier
	s_cbranch_scc1 .LBB0_8
	s_getreg_b32 s3, hwreg(HW_REG_XCC_ID, 0, 4)
	s_and_b32 s3, s3, 15
	v_writelane_b32 v253, s3, 10
	s_and_saveexec_b64 s[12:13], vcc
	s_cbranch_execz .LBB0_7
	s_mov_b64 s[20:21], exec
	v_mbcnt_lo_u32_b32 v1, s20, 0
	v_mbcnt_hi_u32_b32 v1, s21, v1
	v_cmp_eq_u32_e32 vcc, 0, v1
	s_and_saveexec_b64 s[14:15], vcc
	s_cbranch_execz .LBB0_6
	v_readlane_b32 s3, v253, 10
	s_lshl_b32 s3, s3, 8
	s_bcnt1_i32_b64 s4, s[20:21]
	v_mov_b32_e32 v2, s3
	v_mov_b32_e32 v3, s4
	global_atomic_add v2, v2, v3, s[18:19] offset:1024 sc0

; __global__ void __launch_bounds__(NTHREADS, 2) mega_fwd(Args a) {
;     ...
;         if (ph + 1 < a.ph_hi) {
;             const bool local = grouped && (ph == 1 || ph == 5 || ph == 6 || ph == 8 || ph == 12 || ph == 13);
;             if (a.ph_hi > NPHASE) cg::this_grid().sync();
;             else if (local) xcd_barrier_local(xbar);
;             else xcd_barrier(xbar);
.LBB0_10:
	s_xor_b32 s100, s100, 1
	s_cmp_eq_u32 s100, 1
	s_cbranch_scc1 .Lprobe_bar_again
	s_mov_b64 s[0:1], 0

; DI float bflo(unsigned u) { return __uint_as_float(u << 16); }
; DI float bfhi(unsigned u) { return __uint_as_float(u & 0xffff0000u); }
;     DI void fused(f32x4 (&acc)[2][2][4][2], const Unit& u, int wr, int wc, int fr, int fq, LAS unsigned char* lds, int wid, int lane) const {
;     ...
;         const int row0 = u.pm * BM + wr * 64 + fr, col0 = u.pn * BM + wc * 32 + 8 * fq;
; #pragma unroll
;         for (int ai = 0; ai < 2; ++ai)
; #pragma unroll
;             for (int m = 0; m < 4; ++m) {
;                 const size_t off = (size_t)(row0 + ai * HALF + m * 16) * D + col0;
; #pragma unroll
;                 for (int bj = 0; bj < 2; ++bj) {
;                     const u32x4 w = *(const u32x4*)(XB + off + bj * HALF);
;                     const f32x4 x0 = {bflo(w.x), bfhi(w.x), bflo(w.y), bfhi(w.y)}, x1 = {bflo(w.z), bfhi(w.z), bflo(w.w), bfhi(w.w)};
;                     acc[ai][bj][m][0] = x0 * ALPHA + acc[ai][bj][m][0] * s; acc[ai][bj][m][1] = x1 * ALPHA + acc[ai][bj][m][1] * s;
;                 }
;                 asm volatile("" : "+v"(acc[ai][0][m][0]), "+v"(acc[ai][0][m][1]), "+v"(acc[ai][1][m][0]), "+v"(acc[ai][1][m][1]));
;                 if (m & 1) asm volatile("" ::: "memory");
;             }
.LBB0_167:
	s_lshl_b32 s12, s54, 8
	s_add_i32 s1, s12, s11
	s_lshl_b32 s0, s45, 5
	v_or_b32_e32 v98, s1, v145
	s_lshl_b32 s1, s44, 8
	v_lshrrev_b32_e32 v99, 1, v144
	s_or_b32 s0, s1, s0
	v_and_or_b32 v164, v99, 24, s0
	v_ashrrev_i32_e32 v99, 31, v98
	v_readlane_b32 s0, v253, 11
	v_ashrrev_i32_e32 v165, 31, v164
	v_lshlrev_b64 v[108:109], 12, v[98:99]
	v_readlane_b32 s1, v253, 12
	s_mov_b64 s[100:101], s[0:1]
	s_barrier
	s_mov_b32 s4, 0x3fb504f3
	v_lshl_add_u64 v[134:135], s[0:1], 0, v[108:109]
	v_lshlrev_b64 v[108:109], 1, v[164:165]
	v_lshl_add_u64 v[166:167], v[134:135], 0, v[108:109]
	v_lshlrev_b32_e32 v142, 12, v98
	v_lshl_add_u32 v142, v164, 1, v142
	s_nop 4
	global_load_dwordx4 v[218:221], v142, s[100:101]
	global_load_dwordx4 v[222:225], v142, s[100:101] offset:256
	v_add_u32_e32 v143, 0x10000, v142
	global_load_dwordx4 v[226:229], v143, s[100:101]
	global_load_dwordx4 v[230:233], v143, s[100:101] offset:256
	v_add_u32_e32 v146, 0x20000, v142
	global_load_dwordx4 v[234:237], v146, s[100:101]
	global_load_dwordx4 v[238:241], v146, s[100:101] offset:256
	v_add_u32_e32 v147, 0x30000, v142
	global_load_dwordx4 v[242:245], v147, s[100:101]
	global_load_dwordx4 v[148:151], v147, s[100:101] offset:256
	v_add_u32_e32 v143, 0x80000, v142
	global_load_dwordx4 v[152:155], v143, s[100:101]
	global_load_dwordx4 v[156:159], v143, s[100:101] offset:256
	v_add_u32_e32 v146, 0x90000, v142
	global_load_dwordx4 v[184:187], v146, s[100:101]
	v_and_b32_e32 v96, 63, v144
	s_waitcnt vmcnt(10)
	v_mov_b64_e32 v[134:135], v[218:219]
	v_mov_b64_e32 v[136:137], v[220:221]
	global_load_dwordx4 v[218:221], v146, s[100:101] offset:256
	v_lshlrev_b32_e32 v138, 16, v134
	v_and_b32_e32 v139, 0xffff0000, v134
	v_lshlrev_b32_e32 v134, 16, v135
	v_and_b32_e32 v135, 0xffff0000, v135
	v_lshlrev_b32_e32 v140, 16, v136
	v_and_b32_e32 v141, 0xffff0000, v136
	v_lshlrev_b32_e32 v136, 16, v137
	v_and_b32_e32 v137, 0xffff0000, v137
	v_pk_mul_f32 v[134:135], v[134:135], s[4:5] op_sel_hi:[1,0]
	v_pk_mul_f32 v[136:137], v[136:137], s[4:5] op_sel_hi:[1,0]
	v_pk_fma_f32 v[6:7], v[6:7], s[94:95], v[134:135] op_sel_hi:[1,0,1]
	v_pk_mul_f32 v[134:135], v[140:141], s[4:5] op_sel_hi:[1,0]
	v_pk_fma_f32 v[2:3], v[2:3], s[94:95], v[136:137] op_sel_hi:[1,0,1]
	v_pk_fma_f32 v[0:1], v[0:1], s[94:95], v[134:135] op_sel_hi:[1,0,1]
	v_pk_mul_f32 v[138:139], v[138:139], s[4:5] op_sel_hi:[1,0]
	s_waitcnt vmcnt(10)
	v_mov_b64_e32 v[134:135], v[222:223]
	v_mov_b64_e32 v[136:137], v[224:225]
	v_add_u32_e32 v143, 0xa0000, v142
	global_load_dwordx4 v[222:225], v143, s[100:101]
	v_lshlrev_b32_e32 v140, 16, v136
	v_pk_fma_f32 v[4:5], v[4:5], s[94:95], v[138:139] op_sel_hi:[1,0,1]
	v_lshlrev_b32_e32 v138, 16, v134
	v_and_b32_e32 v139, 0xffff0000, v134
	v_lshlrev_b32_e32 v134, 16, v135
	v_and_b32_e32 v135, 0xffff0000, v135
	v_and_b32_e32 v141, 0xffff0000, v136
	v_pk_mul_f32 v[134:135], v[134:135], s[4:5] op_sel_hi:[1,0]
	v_lshlrev_b32_e32 v136, 16, v137
	v_pk_fma_f32 v[14:15], v[14:15], s[94:95], v[134:135] op_sel_hi:[1,0,1]
	v_pk_mul_f32 v[134:135], v[140:141], s[4:5] op_sel_hi:[1,0]
	v_and_b32_e32 v137, 0xffff0000, v137
	v_pk_fma_f32 v[8:9], v[8:9], s[94:95], v[134:135] op_sel_hi:[1,0,1]
	v_or_b32_e32 v134, 16, v98
	v_ashrrev_i32_e32 v135, 31, v134
	v_lshlrev_b64 v[134:135], 12, v[134:135]
	v_pk_mul_f32 v[138:139], v[138:139], s[4:5] op_sel_hi:[1,0]
	v_pk_mul_f32 v[136:137], v[136:137], s[4:5] op_sel_hi:[1,0]
	v_lshl_add_u64 v[134:135], s[0:1], 0, v[134:135]
	v_pk_fma_f32 v[12:13], v[12:13], s[94:95], v[138:139] op_sel_hi:[1,0,1]
	v_pk_fma_f32 v[10:11], v[10:11], s[94:95], v[136:137] op_sel_hi:[1,0,1]
	v_lshl_add_u64 v[168:169], v[134:135], 0, v[108:109]
	s_waitcnt vmcnt(10)
	v_mov_b64_e32 v[134:135], v[226:227]
	v_mov_b64_e32 v[136:137], v[228:229]
	global_load_dwordx4 v[226:229], v143, s[100:101] offset:256
	v_lshlrev_b32_e32 v138, 16, v134
	v_and_b32_e32 v139, 0xffff0000, v134
	v_lshlrev_b32_e32 v134, 16, v135
	v_and_b32_e32 v135, 0xffff0000, v135
	v_lshlrev_b32_e32 v140, 16, v136
	v_and_b32_e32 v141, 0xffff0000, v136
	v_lshlrev_b32_e32 v136, 16, v137
	v_and_b32_e32 v137, 0xffff0000, v137
	v_pk_mul_f32 v[134:135], v[134:135], s[4:5] op_sel_hi:[1,0]
	v_pk_mul_f32 v[136:137], v[136:137], s[4:5] op_sel_hi:[1,0]
	v_pk_fma_f32 v[22:23], v[22:23], s[94:95], v[134:135] op_sel_hi:[1,0,1]
	v_pk_mul_f32 v[134:135], v[140:141], s[4:5] op_sel_hi:[1,0]
	v_pk_fma_f32 v[18:19], v[18:19], s[94:95], v[136:137] op_sel_hi:[1,0,1]
	v_pk_fma_f32 v[16:17], v[16:17], s[94:95], v[134:135] op_sel_hi:[1,0,1]
	v_pk_mul_f32 v[138:139], v[138:139], s[4:5] op_sel_hi:[1,0]
	s_waitcnt vmcnt(10)
	v_mov_b64_e32 v[134:135], v[230:231]
	v_mov_b64_e32 v[136:137], v[232:233]
	v_add_u32_e32 v147, 0xb0000, v142
	global_load_dwordx4 v[230:233], v147, s[100:101]
	v_lshlrev_b32_e32 v140, 16, v136
	v_pk_fma_f32 v[20:21], v[20:21], s[94:95], v[138:139] op_sel_hi:[1,0,1]
	v_lshlrev_b32_e32 v138, 16, v134
	v_and_b32_e32 v139, 0xffff0000, v134
	v_lshlrev_b32_e32 v134, 16, v135
	v_and_b32_e32 v135, 0xffff0000, v135
	v_and_b32_e32 v141, 0xffff0000, v136
	v_pk_mul_f32 v[134:135], v[134:135], s[4:5] op_sel_hi:[1,0]
	v_lshlrev_b32_e32 v136, 16, v137
	v_pk_fma_f32 v[30:31], v[30:31], s[94:95], v[134:135] op_sel_hi:[1,0,1]
	v_pk_mul_f32 v[134:135], v[140:141], s[4:5] op_sel_hi:[1,0]
	v_and_b32_e32 v137, 0xffff0000, v137
	v_pk_fma_f32 v[24:25], v[24:25], s[94:95], v[134:135] op_sel_hi:[1,0,1]
	v_or_b32_e32 v134, 32, v98
	v_ashrrev_i32_e32 v135, 31, v134
	v_pk_mul_f32 v[138:139], v[138:139], s[4:5] op_sel_hi:[1,0]
	v_pk_mul_f32 v[136:137], v[136:137], s[4:5] op_sel_hi:[1,0]
	v_lshlrev_b64 v[134:135], 12, v[134:135]
	v_pk_fma_f32 v[28:29], v[28:29], s[94:95], v[138:139] op_sel_hi:[1,0,1]
	v_pk_fma_f32 v[26:27], v[26:27], s[94:95], v[136:137] op_sel_hi:[1,0,1]
	v_lshl_add_u64 v[134:135], s[0:1], 0, v[134:135]
	v_lshl_add_u64 v[170:171], v[134:135], 0, v[108:109]
	v_or_b32_e32 v98, 48, v98
	v_ashrrev_i32_e32 v99, 31, v98
	v_lshlrev_b64 v[98:99], 12, v[98:99]
	v_lshl_add_u64 v[98:99], s[0:1], 0, v[98:99]
	v_lshl_add_u64 v[172:173], v[98:99], 0, v[108:109]
	s_mov_b64 s[0:1], 0x80000
	v_lshl_add_u64 v[174:175], v[166:167], 0, s[0:1]
	s_mov_b32 s0, 0x80000
	s_waitcnt vmcnt(10)
; DI float bflo(unsigned u) { return __uint_as_float(u << 16); }
; DI float bfhi(unsigned u) { return __uint_as_float(u & 0xffff0000u); }
;     DI void fused(f32x4 (&acc)[2][2][4][2], const Unit& u, int wr, int wc, int fr, int fq, LAS unsigned char* lds, int wid, int lane) const {
;     ...
;         const int row0 = u.pm * BM + wr * 64 + fr, col0 = u.pn * BM + wc * 32 + 8 * fq;
; #pragma unroll
;         for (int ai = 0; ai < 2; ++ai)
; #pragma unroll
;             for (int m = 0; m < 4; ++m) {
;                 const size_t off = (size_t)(row0 + ai * HALF + m * 16) * D + col0;
; #pragma unroll
;                 for (int bj = 0; bj < 2; ++bj) {
;                     const u32x4 w = *(const u32x4*)(XB + off + bj * HALF);
;                     const f32x4 x0 = {bflo(w.x), bfhi(w.x), bflo(w.y), bfhi(w.y)}, x1 = {bflo(w.z), bfhi(w.z), bflo(w.w), bfhi(w.w)};
;                     acc[ai][bj][m][0] = x0 * ALPHA + acc[ai][bj][m][0] * s; acc[ai][bj][m][1] = x1 * ALPHA + acc[ai][bj][m][1] * s;
;                 }
;                 asm volatile("" : "+v"(acc[ai][0][m][0]), "+v"(acc[ai][0][m][1]), "+v"(acc[ai][1][m][0]), "+v"(acc[ai][1][m][1]));
;                 if (m & 1) asm volatile("" ::: "memory");
;             }
	v_mov_b64_e32 v[134:135], v[234:235]
	v_mov_b64_e32 v[136:137], v[236:237]
	global_load_dwordx4 v[234:237], v147, s[100:101] offset:256
	v_lshlrev_b32_e32 v138, 16, v134
	v_and_b32_e32 v139, 0xffff0000, v134
	v_lshlrev_b32_e32 v134, 16, v135
	v_and_b32_e32 v135, 0xffff0000, v135
	v_lshlrev_b32_e32 v140, 16, v136
	v_and_b32_e32 v141, 0xffff0000, v136
	v_lshlrev_b32_e32 v136, 16, v137
	v_and_b32_e32 v137, 0xffff0000, v137
	v_pk_mul_f32 v[134:135], v[134:135], s[4:5] op_sel_hi:[1,0]
	v_pk_mul_f32 v[136:137], v[136:137], s[4:5] op_sel_hi:[1,0]
	v_pk_fma_f32 v[38:39], v[38:39], s[94:95], v[134:135] op_sel_hi:[1,0,1]
	v_pk_mul_f32 v[134:135], v[140:141], s[4:5] op_sel_hi:[1,0]
	v_pk_fma_f32 v[34:35], v[34:35], s[94:95], v[136:137] op_sel_hi:[1,0,1]
	v_pk_fma_f32 v[32:33], v[32:33], s[94:95], v[134:135] op_sel_hi:[1,0,1]
	v_pk_mul_f32 v[138:139], v[138:139], s[4:5] op_sel_hi:[1,0]
	s_waitcnt vmcnt(10)
	v_mov_b64_e32 v[134:135], v[238:239]
	v_mov_b64_e32 v[136:137], v[240:241]
	v_lshlrev_b32_e32 v140, 16, v136
	v_pk_fma_f32 v[36:37], v[36:37], s[94:95], v[138:139] op_sel_hi:[1,0,1]
	v_lshlrev_b32_e32 v138, 16, v134
	v_and_b32_e32 v139, 0xffff0000, v134
	v_lshlrev_b32_e32 v134, 16, v135
	v_and_b32_e32 v135, 0xffff0000, v135
	v_and_b32_e32 v141, 0xffff0000, v136
	v_lshlrev_b32_e32 v136, 16, v137
	v_and_b32_e32 v137, 0xffff0000, v137
	v_pk_mul_f32 v[134:135], v[134:135], s[4:5] op_sel_hi:[1,0]
	v_pk_mul_f32 v[138:139], v[138:139], s[4:5] op_sel_hi:[1,0]
	v_pk_fma_f32 v[46:47], v[46:47], s[94:95], v[134:135] op_sel_hi:[1,0,1]
	v_pk_mul_f32 v[134:135], v[140:141], s[4:5] op_sel_hi:[1,0]
	v_pk_mul_f32 v[136:137], v[136:137], s[4:5] op_sel_hi:[1,0]
	v_pk_fma_f32 v[44:45], v[44:45], s[94:95], v[138:139] op_sel_hi:[1,0,1]
	v_pk_fma_f32 v[42:43], v[42:43], s[94:95], v[136:137] op_sel_hi:[1,0,1]
	v_pk_fma_f32 v[40:41], v[40:41], s[94:95], v[134:135] op_sel_hi:[1,0,1]
	v_add_f32_e32 v139, v14, v15
	v_mov_b32_e32 v138, v9
	s_waitcnt vmcnt(9)
	v_mov_b64_e32 v[134:135], v[242:243]
	v_mov_b64_e32 v[136:137], v[244:245]
	v_lshlrev_b32_e32 v98, 16, v134
	v_and_b32_e32 v99, 0xffff0000, v134
	v_lshlrev_b32_e32 v108, 16, v135
	v_and_b32_e32 v109, 0xffff0000, v135
	v_lshlrev_b32_e32 v134, 16, v136
	v_and_b32_e32 v135, 0xffff0000, v136
	v_lshlrev_b32_e32 v136, 16, v137
	v_and_b32_e32 v137, 0xffff0000, v137
	v_pk_mul_f32 v[98:99], v[98:99], s[4:5] op_sel_hi:[1,0]
	v_pk_mul_f32 v[108:109], v[108:109], s[4:5] op_sel_hi:[1,0]
	v_pk_fma_f32 v[52:53], v[52:53], s[94:95], v[98:99] op_sel_hi:[1,0,1]
	v_pk_fma_f32 v[54:55], v[54:55], s[94:95], v[108:109] op_sel_hi:[1,0,1]
	v_pk_mul_f32 v[98:99], v[134:135], s[4:5] op_sel_hi:[1,0]
	v_pk_mul_f32 v[108:109], v[136:137], s[4:5] op_sel_hi:[1,0]
	v_pk_fma_f32 v[50:51], v[50:51], s[94:95], v[108:109] op_sel_hi:[1,0,1]
	v_pk_fma_f32 v[48:49], v[48:49], s[94:95], v[98:99] op_sel_hi:[1,0,1]
	s_waitcnt vmcnt(8)
	v_mov_b64_e32 v[134:135], v[148:149]
	v_mov_b64_e32 v[136:137], v[150:151]
	v_lshlrev_b32_e32 v98, 16, v134
	v_and_b32_e32 v99, 0xffff0000, v134
	v_lshlrev_b32_e32 v108, 16, v135
	v_and_b32_e32 v109, 0xffff0000, v135
	v_lshlrev_b32_e32 v134, 16, v136
	v_and_b32_e32 v135, 0xffff0000, v136
	v_lshlrev_b32_e32 v136, 16, v137
	v_and_b32_e32 v137, 0xffff0000, v137
	v_pk_mul_f32 v[98:99], v[98:99], s[4:5] op_sel_hi:[1,0]
	v_pk_mul_f32 v[108:109], v[108:109], s[4:5] op_sel_hi:[1,0]
	v_pk_fma_f32 v[60:61], v[60:61], s[94:95], v[98:99] op_sel_hi:[1,0,1]
	v_pk_fma_f32 v[62:63], v[62:63], s[94:95], v[108:109] op_sel_hi:[1,0,1]
	v_pk_mul_f32 v[98:99], v[134:135], s[4:5] op_sel_hi:[1,0]
	v_pk_mul_f32 v[108:109], v[136:137], s[4:5] op_sel_hi:[1,0]
	v_pk_fma_f32 v[56:57], v[56:57], s[94:95], v[98:99] op_sel_hi:[1,0,1]
	v_pk_fma_f32 v[58:59], v[58:59], s[94:95], v[108:109] op_sel_hi:[1,0,1]
	v_add_co_u32_e32 v98, vcc, s0, v166
	s_mov_b64 s[0:1], 0x90000
	s_nop 0
	v_addc_co_u32_e32 v99, vcc, 0, v167, vcc
	v_lshl_add_u64 v[176:177], v[166:167], 0, s[0:1]
	s_mov_b32 s0, 0x90000
	s_waitcnt vmcnt(7)
	v_mov_b64_e32 v[134:135], v[152:153]
	v_mov_b64_e32 v[136:137], v[154:155]
	v_lshlrev_b32_e32 v98, 16, v134
	v_and_b32_e32 v99, 0xffff0000, v134
	v_lshlrev_b32_e32 v108, 16, v135
	v_and_b32_e32 v109, 0xffff0000, v135
	v_lshlrev_b32_e32 v134, 16, v136
	v_and_b32_e32 v135, 0xffff0000, v136
	v_lshlrev_b32_e32 v136, 16, v137
	v_and_b32_e32 v137, 0xffff0000, v137
	v_pk_mul_f32 v[98:99], v[98:99], s[4:5] op_sel_hi:[1,0]
	v_pk_mul_f32 v[108:109], v[108:109], s[4:5] op_sel_hi:[1,0]
	v_pk_fma_f32 v[68:69], v[68:69], s[94:95], v[98:99] op_sel_hi:[1,0,1]
	v_pk_fma_f32 v[70:71], v[70:71], s[94:95], v[108:109] op_sel_hi:[1,0,1]
	v_pk_mul_f32 v[98:99], v[134:135], s[4:5] op_sel_hi:[1,0]
	v_pk_mul_f32 v[108:109], v[136:137], s[4:5] op_sel_hi:[1,0]
	v_pk_fma_f32 v[64:65], v[64:65], s[94:95], v[98:99] op_sel_hi:[1,0,1]
	v_pk_fma_f32 v[66:67], v[66:67], s[94:95], v[108:109] op_sel_hi:[1,0,1]
	s_waitcnt vmcnt(6)
	v_mov_b64_e32 v[134:135], v[156:157]
	v_mov_b64_e32 v[136:137], v[158:159]
	v_lshlrev_b32_e32 v98, 16, v134
	v_and_b32_e32 v99, 0xffff0000, v134
	v_lshlrev_b32_e32 v108, 16, v135
	v_and_b32_e32 v109, 0xffff0000, v135
	v_lshlrev_b32_e32 v134, 16, v136
	v_and_b32_e32 v135, 0xffff0000, v136
	v_pk_mul_f32 v[98:99], v[98:99], s[4:5] op_sel_hi:[1,0]
	v_lshlrev_b32_e32 v136, 16, v137
	v_and_b32_e32 v137, 0xffff0000, v137
	v_pk_mul_f32 v[108:109], v[108:109], s[4:5] op_sel_hi:[1,0]
	v_pk_fma_f32 v[76:77], v[76:77], s[94:95], v[98:99] op_sel_hi:[1,0,1]
	v_pk_mul_f32 v[98:99], v[134:135], s[4:5] op_sel_hi:[1,0]
	v_pk_fma_f32 v[78:79], v[78:79], s[94:95], v[108:109] op_sel_hi:[1,0,1]
	v_pk_mul_f32 v[108:109], v[136:137], s[4:5] op_sel_hi:[1,0]
	v_pk_fma_f32 v[72:73], v[72:73], s[94:95], v[98:99] op_sel_hi:[1,0,1]
	v_add_co_u32_e32 v98, vcc, s0, v166
	v_pk_fma_f32 v[74:75], v[74:75], s[94:95], v[108:109] op_sel_hi:[1,0,1]
	s_nop 0
	v_addc_co_u32_e32 v99, vcc, 0, v167, vcc
	s_mov_b64 s[0:1], 0xa0000
	v_lshl_add_u64 v[178:179], v[166:167], 0, s[0:1]
	s_mov_b32 s0, 0xa0000
	s_waitcnt vmcnt(5)
; DI float bflo(unsigned u) { return __uint_as_float(u << 16); }
; DI float bfhi(unsigned u) { return __uint_as_float(u & 0xffff0000u); }
;     DI void fused(f32x4 (&acc)[2][2][4][2], const Unit& u, int wr, int wc, int fr, int fq, LAS unsigned char* lds, int wid, int lane) const {
;     ...
;         const int row0 = u.pm * BM + wr * 64 + fr, col0 = u.pn * BM + wc * 32 + 8 * fq;
; #pragma unroll
;         for (int ai = 0; ai < 2; ++ai)
; #pragma unroll
;             for (int m = 0; m < 4; ++m) {
;                 const size_t off = (size_t)(row0 + ai * HALF + m * 16) * D + col0;
; #pragma unroll
;                 for (int bj = 0; bj < 2; ++bj) {
;                     const u32x4 w = *(const u32x4*)(XB + off + bj * HALF);
;                     const f32x4 x0 = {bflo(w.x), bfhi(w.x), bflo(w.y), bfhi(w.y)}, x1 = {bflo(w.z), bfhi(w.z), bflo(w.w), bfhi(w.w)};
;                     acc[ai][bj][m][0] = x0 * ALPHA + acc[ai][bj][m][0] * s; acc[ai][bj][m][1] = x1 * ALPHA + acc[ai][bj][m][1] * s;
;                 }
;                 asm volatile("" : "+v"(acc[ai][0][m][0]), "+v"(acc[ai][0][m][1]), "+v"(acc[ai][1][m][0]), "+v"(acc[ai][1][m][1]));
;                 if (m & 1) asm volatile("" ::: "memory");
;             }
	v_mov_b64_e32 v[134:135], v[184:185]
	v_mov_b64_e32 v[136:137], v[186:187]
	v_lshlrev_b32_e32 v98, 16, v134
	v_and_b32_e32 v99, 0xffff0000, v134
	v_lshlrev_b32_e32 v108, 16, v135
	v_and_b32_e32 v109, 0xffff0000, v135
	v_lshlrev_b32_e32 v134, 16, v136
	v_and_b32_e32 v135, 0xffff0000, v136
	v_lshlrev_b32_e32 v136, 16, v137
	v_and_b32_e32 v137, 0xffff0000, v137
	v_pk_mul_f32 v[98:99], v[98:99], s[4:5] op_sel_hi:[1,0]
	v_pk_mul_f32 v[108:109], v[108:109], s[4:5] op_sel_hi:[1,0]
	v_pk_fma_f32 v[84:85], v[84:85], s[94:95], v[98:99] op_sel_hi:[1,0,1]
	v_pk_fma_f32 v[86:87], v[86:87], s[94:95], v[108:109] op_sel_hi:[1,0,1]
	v_pk_mul_f32 v[98:99], v[134:135], s[4:5] op_sel_hi:[1,0]
	v_pk_mul_f32 v[108:109], v[136:137], s[4:5] op_sel_hi:[1,0]
	v_pk_fma_f32 v[82:83], v[82:83], s[94:95], v[108:109] op_sel_hi:[1,0,1]
	v_pk_fma_f32 v[80:81], v[80:81], s[94:95], v[98:99] op_sel_hi:[1,0,1]
	s_waitcnt vmcnt(4)
	v_mov_b64_e32 v[134:135], v[218:219]
	v_mov_b64_e32 v[136:137], v[220:221]
	v_lshlrev_b32_e32 v98, 16, v134
	v_and_b32_e32 v99, 0xffff0000, v134
	v_lshlrev_b32_e32 v108, 16, v135
	v_and_b32_e32 v109, 0xffff0000, v135
	v_lshlrev_b32_e32 v134, 16, v136
	v_and_b32_e32 v135, 0xffff0000, v136
	v_lshlrev_b32_e32 v136, 16, v137
	v_and_b32_e32 v137, 0xffff0000, v137
	v_pk_mul_f32 v[98:99], v[98:99], s[4:5] op_sel_hi:[1,0]
	v_pk_mul_f32 v[108:109], v[108:109], s[4:5] op_sel_hi:[1,0]
	v_pk_fma_f32 v[92:93], v[92:93], s[94:95], v[98:99] op_sel_hi:[1,0,1]
	v_pk_fma_f32 v[94:95], v[94:95], s[94:95], v[108:109] op_sel_hi:[1,0,1]
	v_pk_mul_f32 v[98:99], v[134:135], s[4:5] op_sel_hi:[1,0]
	v_pk_mul_f32 v[108:109], v[136:137], s[4:5] op_sel_hi:[1,0]
	v_pk_fma_f32 v[88:89], v[88:89], s[94:95], v[98:99] op_sel_hi:[1,0,1]
	v_pk_fma_f32 v[90:91], v[90:91], s[94:95], v[108:109] op_sel_hi:[1,0,1]
	v_add_co_u32_e32 v98, vcc, s0, v166
	s_mov_b64 s[0:1], 0xb0000
	s_nop 0
	v_addc_co_u32_e32 v99, vcc, 0, v167, vcc
	v_lshl_add_u64 v[180:181], v[166:167], 0, s[0:1]
	s_mov_b32 s0, 0xb0000
	s_waitcnt vmcnt(3)
	v_mov_b64_e32 v[134:135], v[222:223]
	v_mov_b64_e32 v[136:137], v[224:225]
	v_lshlrev_b32_e32 v98, 16, v134
	v_and_b32_e32 v99, 0xffff0000, v134
	v_lshlrev_b32_e32 v108, 16, v135
	v_and_b32_e32 v109, 0xffff0000, v135
	v_lshlrev_b32_e32 v134, 16, v136
	v_and_b32_e32 v135, 0xffff0000, v136
	v_lshlrev_b32_e32 v136, 16, v137
	v_and_b32_e32 v137, 0xffff0000, v137
	v_pk_mul_f32 v[98:99], v[98:99], s[4:5] op_sel_hi:[1,0]
	v_pk_mul_f32 v[108:109], v[108:109], s[4:5] op_sel_hi:[1,0]
	v_pk_fma_f32 v[114:115], v[114:115], s[94:95], v[98:99] op_sel_hi:[1,0,1]
	v_pk_fma_f32 v[116:117], v[116:117], s[94:95], v[108:109] op_sel_hi:[1,0,1]
	v_pk_mul_f32 v[98:99], v[134:135], s[4:5] op_sel_hi:[1,0]
	v_pk_mul_f32 v[108:109], v[136:137], s[4:5] op_sel_hi:[1,0]
	v_pk_fma_f32 v[108:109], v[106:107], s[94:95], v[108:109] op_sel_hi:[1,0,1]
	v_pk_fma_f32 v[106:107], v[104:105], s[94:95], v[98:99] op_sel_hi:[1,0,1]
	s_waitcnt vmcnt(2)
	v_mov_b64_e32 v[134:135], v[226:227]
	v_mov_b64_e32 v[136:137], v[228:229]
	v_lshlrev_b32_e32 v98, 16, v134
	v_and_b32_e32 v99, 0xffff0000, v134
	v_lshlrev_b32_e32 v104, 16, v135
	v_and_b32_e32 v105, 0xffff0000, v135
	v_lshlrev_b32_e32 v134, 16, v136
	v_and_b32_e32 v135, 0xffff0000, v136
	v_pk_mul_f32 v[98:99], v[98:99], s[4:5] op_sel_hi:[1,0]
	v_lshlrev_b32_e32 v136, 16, v137
	v_and_b32_e32 v137, 0xffff0000, v137
	v_pk_mul_f32 v[104:105], v[104:105], s[4:5] op_sel_hi:[1,0]
	v_pk_fma_f32 v[126:127], v[126:127], s[94:95], v[98:99] op_sel_hi:[1,0,1]
	v_pk_mul_f32 v[98:99], v[134:135], s[4:5] op_sel_hi:[1,0]
	v_pk_fma_f32 v[128:129], v[128:129], s[94:95], v[104:105] op_sel_hi:[1,0,1]
	v_pk_mul_f32 v[104:105], v[136:137], s[4:5] op_sel_hi:[1,0]
	v_pk_fma_f32 v[122:123], v[122:123], s[94:95], v[98:99] op_sel_hi:[1,0,1]
	v_add_co_u32_e32 v98, vcc, s0, v166
	v_pk_fma_f32 v[124:125], v[124:125], s[94:95], v[104:105] op_sel_hi:[1,0,1]
	s_nop 0
	v_addc_co_u32_e32 v99, vcc, 0, v167, vcc
	s_lshl_b32 s0, s45, 3
	s_add_i32 s0, s0, 0
	s_waitcnt vmcnt(1)
; DI float bflo(unsigned u) { return __uint_as_float(u << 16); }
; DI float bfhi(unsigned u) { return __uint_as_float(u & 0xffff0000u); }
;     DI void fused(f32x4 (&acc)[2][2][4][2], const Unit& u, int wr, int wc, int fr, int fq, LAS unsigned char* lds, int wid, int lane) const {
;     ...
;                 for (int bj = 0; bj < 2; ++bj) {
;                     const u32x4 w = *(const u32x4*)(XB + off + bj * HALF);
;                     const f32x4 x0 = {bflo(w.x), bfhi(w.x), bflo(w.y), bfhi(w.y)}, x1 = {bflo(w.z), bfhi(w.z), bflo(w.w), bfhi(w.w)};
;                     acc[ai][bj][m][0] = x0 * ALPHA + acc[ai][bj][m][0] * s; acc[ai][bj][m][1] = x1 * ALPHA + acc[ai][bj][m][1] * s;
;                 }
;                 asm volatile("" : "+v"(acc[ai][0][m][0]), "+v"(acc[ai][0][m][1]), "+v"(acc[ai][1][m][0]), "+v"(acc[ai][1][m][1]));
;                 if (m & 1) asm volatile("" ::: "memory");
;             }
; #pragma unroll
;         for (int ai = 0; ai < 2; ++ai)
; #pragma unroll
;             for (int m = 0; m < 4; ++m) {
;                 float sm = 0.f;
; #pragma unroll
;                 for (int bj = 0; bj < 2; ++bj)
; #pragma unroll
;                     for (int n = 0; n < 2; ++n) { const f32x4 x = acc[ai][bj][m][n]; sm += (x[0] + x[1]) + (x[2] + x[3]); }
;                 sm += __shfl_xor(sm, 16); sm += __shfl_xor(sm, 32);
;                 const float mw = sm * (1.0f / 64.0f); float q = 0.f;
; #pragma unroll
;                 for (int bj = 0; bj < 2; ++bj)
; #pragma unroll
;                     for (int n = 0; n < 2; ++n) { const f32x4 d = acc[ai][bj][m][n] - mw; q += (d[0] * d[0] + d[1] * d[1]) + (d[2] * d[2] + d[3] * d[3]); }
;                 q += __shfl_xor(q, 16); q += __shfl_xor(q, 32);
;                 if (fq == 0) P[(ai * HALF + wr * 64 + m * 16 + fr) * 4 + wc] = (f32x2v){mw, q};
	v_mov_b64_e32 v[134:135], v[230:231]
	v_mov_b64_e32 v[136:137], v[232:233]
	v_lshlrev_b32_e32 v98, 16, v134
	v_and_b32_e32 v99, 0xffff0000, v134
	v_lshlrev_b32_e32 v104, 16, v135
	v_and_b32_e32 v105, 0xffff0000, v135
	v_lshlrev_b32_e32 v134, 16, v136
	v_and_b32_e32 v135, 0xffff0000, v136
	v_lshlrev_b32_e32 v136, 16, v137
	v_and_b32_e32 v137, 0xffff0000, v137
	v_pk_mul_f32 v[98:99], v[98:99], s[4:5] op_sel_hi:[1,0]
	v_pk_mul_f32 v[104:105], v[104:105], s[4:5] op_sel_hi:[1,0]
	v_pk_fma_f32 v[118:119], v[118:119], s[94:95], v[98:99] op_sel_hi:[1,0,1]
	v_pk_fma_f32 v[120:121], v[120:121], s[94:95], v[104:105] op_sel_hi:[1,0,1]
	v_pk_mul_f32 v[98:99], v[134:135], s[4:5] op_sel_hi:[1,0]
	v_pk_mul_f32 v[104:105], v[136:137], s[4:5] op_sel_hi:[1,0]
	v_pk_fma_f32 v[112:113], v[112:113], s[94:95], v[104:105] op_sel_hi:[1,0,1]
	v_pk_fma_f32 v[110:111], v[110:111], s[94:95], v[98:99] op_sel_hi:[1,0,1]
	s_waitcnt vmcnt(0)
	v_mov_b64_e32 v[134:135], v[234:235]
	v_mov_b64_e32 v[136:137], v[236:237]
	v_lshlrev_b32_e32 v98, 16, v134
	v_and_b32_e32 v99, 0xffff0000, v134
	v_lshlrev_b32_e32 v104, 16, v135
	v_and_b32_e32 v105, 0xffff0000, v135
	v_lshlrev_b32_e32 v134, 16, v136
	v_and_b32_e32 v135, 0xffff0000, v136
	v_pk_mul_f32 v[98:99], v[98:99], s[4:5] op_sel_hi:[1,0]
	v_pk_mul_f32 v[104:105], v[104:105], s[4:5] op_sel_hi:[1,0]
	v_lshlrev_b32_e32 v136, 16, v137
	v_and_b32_e32 v137, 0xffff0000, v137
	v_pk_fma_f32 v[104:105], v[102:103], s[94:95], v[104:105] op_sel_hi:[1,0,1]
	v_pk_fma_f32 v[102:103], v[100:101], s[94:95], v[98:99] op_sel_hi:[1,0,1]
	v_pk_mul_f32 v[98:99], v[134:135], s[4:5] op_sel_hi:[1,0]
	v_pk_mul_f32 v[100:101], v[136:137], s[4:5] op_sel_hi:[1,0]
	v_pk_fma_f32 v[98:99], v[130:131], s[94:95], v[98:99] op_sel_hi:[1,0,1]
	v_mbcnt_hi_u32_b32 v131, -1, v190
	v_pk_fma_f32 v[100:101], v[132:133], s[94:95], v[100:101] op_sel_hi:[1,0,1]
	v_and_b32_e32 v132, 64, v131
	v_xor_b32_e32 v130, 16, v131
	v_add_u32_e32 v132, 64, v132
	v_cmp_lt_i32_e32 vcc, v130, v132
	v_xor_b32_e32 v133, 32, v131
	v_mov_b32_e32 v134, v4
	v_cndmask_b32_e32 v130, v131, v130, vcc
	v_cmp_lt_i32_e32 vcc, v133, v132
	v_mov_b32_e32 v132, v5
	v_mov_b32_e32 v135, v7
	v_cndmask_b32_e32 v131, v131, v133, vcc
	v_mov_b32_e32 v133, v6
	v_pk_add_f32 v[132:133], v[132:133], v[134:135]
	v_mov_b32_e32 v134, v1
	v_mov_b32_e32 v135, v2
	v_mov_b32_e32 v136, v0
	v_mov_b32_e32 v137, v3
	v_pk_add_f32 v[134:135], v[134:135], v[136:137]
	v_add_f32_e32 v132, v132, v133
	v_pk_add_f32 v[134:135], v[134:135], v[134:135] op_sel_hi:[0,1]
	v_add_f32_e32 v133, 0, v132
	v_add_f32_e32 v137, v12, v13
	v_mov_b32_e32 v136, v8
	v_mov_b32_e32 v134, v10
	v_mov_b32_e32 v132, v11
	v_pk_add_f32 v[136:137], v[136:137], v[138:139]
	v_pk_add_f32 v[132:133], v[134:135], v[132:133]
	v_lshlrev_b32_e32 v130, 2, v130
	v_pk_add_f32 v[132:133], v[136:137], v[132:133]
	v_lshlrev_b32_e32 v131, 2, v131
	v_add_f32_e32 v132, v132, v133
	ds_bpermute_b32 v133, v130, v132
	v_cmp_gt_u32_e32 vcc, 16, v96
	s_waitcnt lgkmcnt(0)
	v_add_f32_e32 v132, v132, v133
	ds_bpermute_b32 v133, v131, v132
	s_waitcnt lgkmcnt(0)
	v_add_f32_e32 v133, v132, v133
	v_fmamk_f32 v134, v133, 0xbc800000, v7
	v_fmamk_f32 v136, v133, 0xbc800000, v5
	v_fmamk_f32 v132, v133, 0xbc800000, v6
	v_fmamk_f32 v135, v133, 0xbc800000, v4
	v_mul_f32_e32 v136, v136, v136
	v_mul_f32_e32 v134, v134, v134
	v_fmac_f32_e32 v136, v135, v135
	v_fmac_f32_e32 v134, v132, v132
	v_fmamk_f32 v135, v133, 0xbc800000, v3
	v_fmamk_f32 v137, v133, 0xbc800000, v1
	v_add_f32_e32 v132, v136, v134
	v_fmamk_f32 v134, v133, 0xbc800000, v2
	v_fmamk_f32 v136, v133, 0xbc800000, v0
	v_mul_f32_e32 v137, v137, v137
	v_mul_f32_e32 v135, v135, v135
	v_fmac_f32_e32 v137, v136, v136
	v_fmac_f32_e32 v135, v134, v134
	v_add_f32_e32 v134, v137, v135
	v_fmamk_f32 v135, v133, 0xbc800000, v15
	v_fmamk_f32 v137, v133, 0xbc800000, v13
	v_add_f32_e32 v132, v132, v134
	v_fmamk_f32 v134, v133, 0xbc800000, v14
	v_fmamk_f32 v136, v133, 0xbc800000, v12
	v_mul_f32_e32 v137, v137, v137
	v_mul_f32_e32 v135, v135, v135
	v_fmac_f32_e32 v137, v136, v136
	v_fmac_f32_e32 v135, v134, v134
	v_add_f32_e32 v134, v137, v135
	v_fmamk_f32 v135, v133, 0xbc800000, v11
	v_fmamk_f32 v137, v133, 0xbc800000, v9
	v_add_f32_e32 v132, v134, v132
	v_fmamk_f32 v134, v133, 0xbc800000, v10
	v_fmamk_f32 v136, v133, 0xbc800000, v8
	v_mul_f32_e32 v137, v137, v137
	v_mul_f32_e32 v135, v135, v135
	v_fmac_f32_e32 v137, v136, v136
	v_fmac_f32_e32 v135, v134, v134
	v_add_f32_e32 v134, v137, v135
	v_add_f32_e32 v132, v134, v132
	ds_bpermute_b32 v134, v130, v132
	s_waitcnt lgkmcnt(0)
	v_add_f32_e32 v134, v132, v134
	ds_bpermute_b32 v135, v131, v134
	v_lshl_add_u32 v132, v216, 5, s0
	s_and_saveexec_b64 s[0:1], vcc
	s_mov_b32 s55, s84
	v_readlane_b32 s6, v255, 16
	v_readlane_b32 s7, v255, 17
	s_cbranch_execz .LBB0_169
	v_mul_f32_e32 v136, 0x3c800000, v133
	s_waitcnt lgkmcnt(0)
	v_add_f32_e32 v137, v134, v135
	ds_write_b64 v132, v[136:137]

; __global__ void __launch_bounds__(NTHREADS, 2) mega_fwd(Args a) {
;     ...
;         if (ph + 1 < a.ph_hi) {
;             const bool local = grouped && (ph == 1 || ph == 5 || ph == 6 || ph == 8 || ph == 12 || ph == 13);
;             if (a.ph_hi > NPHASE) cg::this_grid().sync();
;             else if (local) xcd_barrier_local(xbar);
;             else xcd_barrier(xbar);
.Lprobe_bar_again:
	v_readlane_b32 s0, v255, 4
	s_cmp_gt_u32 s33, 13
	v_readlane_b32 s1, v255, 5
	s_cselect_b64 s[4:5], -1, 0
	s_xor_b64 s[6:7], s[0:1], -1
	s_or_b64 s[4:5], s[6:7], s[4:5]
	s_mov_b64 s[0:1], 0
	s_and_b64 vcc, exec, s[4:5]
	s_cbranch_vccnz .LBB0_562
	s_lshr_b32 s0, 0x3162, s33
	s_bitcmp1_b32 s0, 0
	s_cselect_b64 s[0:1], -1, 0

; __global__ void __launch_bounds__(NTHREADS, 2) mega_fwd(Args a) {
	.amdhsa_kernel _Z8mega_fwd4Args
		.amdhsa_group_segment_fixed_size 0
		.amdhsa_private_segment_fixed_size 0
		.amdhsa_kernarg_size 384
		.amdhsa_user_sgpr_count 2
		.amdhsa_user_sgpr_dispatch_ptr 0
		.amdhsa_user_sgpr_queue_ptr 0
		.amdhsa_user_sgpr_kernarg_segment_ptr 1
		.amdhsa_user_sgpr_dispatch_id 0
		.amdhsa_user_sgpr_kernarg_preload_length 0
		.amdhsa_user_sgpr_kernarg_preload_offset 0
		.amdhsa_user_sgpr_private_segment_size 0
		.amdhsa_uses_dynamic_stack 0
		.amdhsa_enable_private_segment 0
		.amdhsa_system_sgpr_workgroup_id_x 1
		.amdhsa_system_sgpr_workgroup_id_y 0
		.amdhsa_system_sgpr_workgroup_id_z 0
		.amdhsa_system_sgpr_workgroup_info 0
		.amdhsa_system_vgpr_workitem_id 2
		.amdhsa_next_free_vgpr 256
		.amdhsa_next_free_sgpr 102
		.amdhsa_accum_offset 256
		.amdhsa_reserve_vcc 1
		.amdhsa_float_round_mode_32 0
		.amdhsa_float_round_mode_16_64 0
		.amdhsa_float_denorm_mode_32 3
		.amdhsa_float_denorm_mode_16_64 3
		.amdhsa_dx10_clamp 1
		.amdhsa_ieee_mode 1
		.amdhsa_fp16_overflow 0
		.amdhsa_tg_split 0
		.amdhsa_exception_fp_ieee_invalid_op 0
		.amdhsa_exception_fp_denorm_src 0
		.amdhsa_exception_fp_ieee_div_zero 0
		.amdhsa_exception_fp_ieee_overflow 0
		.amdhsa_exception_fp_ieee_underflow 0
		.amdhsa_exception_fp_ieee_inexact 0
		.amdhsa_exception_int_div_zero 0
	.end_amdhsa_kernel

; __global__ void __launch_bounds__(NTHREADS, 2) mega_fwd(Args a) {
amdhsa.kernels:
  - .agpr_count:     0
    .args:
      - .offset:         0
        .size:           128
        .value_kind:     by_value
      - .offset:         128
        .size:           4
        .value_kind:     hidden_block_count_x
      - .offset:         132
        .size:           4
        .value_kind:     hidden_block_count_y
      - .offset:         136
        .size:           4
        .value_kind:     hidden_block_count_z
      - .offset:         140
        .size:           2
        .value_kind:     hidden_group_size_x
      - .offset:         142
        .size:           2
        .value_kind:     hidden_group_size_y
      - .offset:         144
        .size:           2
        .value_kind:     hidden_group_size_z
      - .offset:         146
        .size:           2
        .value_kind:     hidden_remainder_x
      - .offset:         148
        .size:           2
        .value_kind:     hidden_remainder_y
      - .offset:         150
        .size:           2
        .value_kind:     hidden_remainder_z
      - .offset:         168
        .size:           8
        .value_kind:     hidden_global_offset_x
      - .offset:         176
        .size:           8
        .value_kind:     hidden_global_offset_y
      - .offset:         184
        .size:           8
        .value_kind:     hidden_global_offset_z
      - .offset:         192
        .size:           2
        .value_kind:     hidden_grid_dims
      - .offset:         216
        .size:           8
        .value_kind:     hidden_multigrid_sync_arg
      - .offset:         248
        .size:           4
        .value_kind:     hidden_dynamic_lds_size
    .group_segment_fixed_size: 0
    .kernarg_segment_align: 8
    .kernarg_segment_size: 384
    .language:       OpenCL C
    .language_version:
      - 2
      - 0
    .max_flat_workgroup_size: 512
    .name:           _Z8mega_fwd4Args
    .private_segment_fixed_size: 0
    .sgpr_count:     108
    .sgpr_spill_count: 159
    .symbol:         _Z8mega_fwd4Args.kd
    .uniform_work_group_size: 1
    .uses_dynamic_stack: false
    .vgpr_count:     256
    .vgpr_spill_count: 0
    .wavefront_size: 64
